# prep: prefetch (dummy load) of the next transpose tile at the item-loop latch so its loads hit L2
# speedup vs baseline: 1.0205x; 1.0024x over previous
; DEV int tidx() { int t = threadIdx.x; asm volatile("" : "+v"(t)); return t; }
; DEV void phase_prep(const Params& p, char* smem) {
;   for (int item = blockIdx.x; item < P0_ITEMS; item += gridDim.x) {
;     int it = item;
;     if (it < P0_TR) {
;       if (it < NT_WIN) { transpose_tile(p.in[I_WIN], 1024, 1440, WSP(bf16_t, S_WIN0), LDH, it, smem); continue; }
;       it -= NT_WIN;
;       if (it < NT_WUQ) { transpose_tile(p.in[I_WUQ], 256, 768, WSP(bf16_t, S_WUQ), 256, it, smem); continue; }
;       it -= NT_WUQ;
;       if (it < NT_WUKV) { transpose_tile(p.in[I_WUKV], 128, 1024, WSP(bf16_t, S_WUKV), 128, it, smem); continue; }
;       it -= NT_WUKV;
;       if (it < NT_WOUT) { transpose_tile(p.in[I_WOUT], 1024, 1024, WSP(bf16_t, S_WOUT0), LDH, it, smem); continue; }
;       it -= NT_WOUT;
;       if (it < NT_HGIN) { transpose_tile(p.in[I_HGWIN], 1024, 5120, WSP(bf16_t, S_WHGIN), LDH, it, smem); continue; }
;       it -= NT_HGIN;
;       if (it < NT_HGOUT) { transpose_tile(p.in[I_HGWOUT], 1024, 1024, WSP(bf16_t, S_WHGOUT), LDH, it, smem); continue; }
;       it -= NT_HGOUT;
;       int l = it >> 11; it &= 2047;
;       transpose_tile(p.in[I_PWQ] + (size_t)l * 1024 * 2048, 1024, 2048, WSP(bf16_t, S_WPQ) + (size_t)l * 2048 * LDH, LDH, it, smem);
;     ...
;     {
;       int idx = it * 256 + tidx();
;       int t = idx >> 4, i = idx & 15;
;       int f = i & 7;
;       float pos = (i < 8) ? (float)(t >> 6) : (float)(t & 63);
;       float inv = powf(10000.f, -(float)(2 * f) / 16.f);
;       float ang = pos * inv;
;       WSP(float, S_ROPEC)[idx] = cosf(ang);
;       WSP(float, S_ROPES)[idx] = sinf(ang);
.Lp0_set:
	s_lshl_b32 s12, s12, 9
	s_or_b32 s49, s12, s13
	s_add_i32 s48, s49, 0xffffbbed
	s_add_i32 s16, m0, 0x200
	s_lshr_b32 s16, s16, 9
	s_cmp_lt_u32 s16, 32
	s_cbranch_scc0 .Lp0_pf_done
	s_and_b32 s17, s16, 3
	s_cmp_eq_u32 s17, 3
	s_cbranch_scc1 .Lp0_pf_done
	s_lshr_b32 s16, s16, 2
	s_mul_i32 s16, s16, 3
	s_add_u32 s16, s16, s17
	s_lshl_b32 s16, s16, 9
	s_or_b32 s16, s16, s13
	s_mov_b32 s38, 0
	s_cmpk_lt_u32 s16, 0x5a0
	s_cbranch_scc0 .Lp0_pf_1
	s_mul_i32 s39, s16, 1457
	s_lshr_b32 s39, s39, 16
	s_mul_i32 s40, s39, 45
	s_sub_u32 s40, s16, s40
	s_movk_i32 s12, 0x1680
	s_movk_i32 s17, 0x40
	s_branch .Lp0_pf_go
.Lp0_pf_1:
	s_cmpk_lt_u32 s16, 0x660
	s_cbranch_scc0 .Lp0_pf_2
	s_sub_u32 s16, s16, 1440
	s_mul_i32 s39, s16, 171
	s_lshr_b32 s39, s39, 12
	s_mul_i32 s40, s39, 24
	s_sub_u32 s40, s16, s40
	s_movk_i32 s12, 0xc00
	s_movk_i32 s17, 0x50
	s_branch .Lp0_pf_go
.Lp0_pf_2:
	s_cmpk_lt_u32 s16, 0x6e0
	s_cbranch_scc0 .Lp0_pf_3
	s_sub_u32 s16, s16, 1632
	s_movk_i32 s17, 0x60
	s_branch .Lp0_pf_p32
.Lp0_pf_3:
	s_cmpk_lt_u32 s16, 0xae0
	s_cbranch_scc0 .Lp0_pf_4
	s_sub_u32 s16, s16, 1760
	s_movk_i32 s17, 0x88
	s_branch .Lp0_pf_p32
.Lp0_pf_4:
	s_cmpk_lt_u32 s16, 0x1ee0
	s_cbranch_scc0 .Lp0_pf_5
	s_sub_u32 s16, s16, 2784
	s_mul_i32 s39, s16, 3277
	s_lshr_b32 s39, s39, 19
	s_mul_i32 s40, s39, 160
	s_sub_u32 s40, s16, s40
	s_movk_i32 s12, 0x5000
	s_movk_i32 s17, 0x90
	s_branch .Lp0_pf_go
.Lp0_pf_5:
	s_cmpk_lt_u32 s16, 0x22e0
	s_cbranch_scc0 .Lp0_pf_6
	s_sub_u32 s16, s16, 7904
	s_movk_i32 s17, 0xa8
.Lp0_pf_p32:
	s_lshr_b32 s39, s16, 5
	s_and_b32 s40, s16, 31
	s_movk_i32 s12, 0x1000
	s_branch .Lp0_pf_go
.Lp0_pf_6:
	s_sub_u32 s16, s16, 8928
	s_lshr_b32 s38, s16, 11
	s_lshl_b32 s38, s38, 23
	s_and_b32 s16, s16, 0x7ff
	s_lshr_b32 s39, s16, 6
	s_and_b32 s40, s16, 63
	s_movk_i32 s12, 0x2000
	s_movk_i32 s17, 0xb0
.Lp0_pf_go:
	s_mul_i32 s39, s39, s12
	s_lshl_b32 s39, s39, 5
	s_lshl_b32 s40, s40, 7
	s_add_u32 s39, s39, s40
	s_add_u32 s39, s39, s38
	s_add_u32 s17, s17, 0x13b00
	v_mov_b32_e32 v88, s17
	ds_read_b64 v[88:89], v88
	v_lshrrev_b32_e32 v90, 3, v195
	v_mul_u32_u24_e32 v90, s12, v90
	v_and_b32_e32 v91, 7, v195
	v_lshl_add_u32 v90, v91, 4, v90
	v_add_u32_e32 v90, s39, v90
	v_mov_b32_e32 v91, 0
	s_waitcnt lgkmcnt(0)
	v_lshl_add_u64 v[88:89], v[88:89], 0, v[90:91]
	global_load_dwordx4 v[84:87], v[88:89], off
.Lp0_pf_done:
.LBB0_1066:
	s_cmpk_gt_i32 s49, 0x32df
	s_mov_b64 s[12:13], -1
	s_cbranch_scc0 .LBB0_1110
	s_cmpk_gt_u32 s49, 0x33df
	s_cbranch_scc0 .LBB0_1107
	s_cmpk_gt_u32 s49, 0x43df
	s_cbranch_scc0 .LBB0_1096
	s_cmpk_gt_u32 s49, 0x4412
	s_cbranch_scc0 .LBB0_1093
	s_cmpk_gt_u32 s49, 0x4592
	s_cbranch_scc0 .LBB0_1084
	s_lshl_b32 s12, s49, 8
	v_mov_b32_e32 v3, v195
	s_add_i32 s12, s12, 0xffba6d00
	s_nop 0
	v_and_b32_e32 v0, 8, v3
	v_add_u32_e32 v2, s12, v3
	v_cmp_ne_u32_e32 vcc, 0, v0
	s_and_saveexec_b64 s[12:13], vcc
	s_xor_b64 s[12:13], exec, s[12:13]
	v_bfe_u32 v0, v2, 4, 6
	v_cvt_f32_ubyte0_e32 v0, v0
	s_andn2_saveexec_b64 s[12:13], s[12:13]
	v_ashrrev_i32_e32 v0, 10, v2
	v_cvt_f32_i32_e32 v0, v0
	s_or_b64 exec, exec, s[12:13]
	v_lshlrev_b32_e32 v3, 1, v3
	v_and_b32_e32 v3, 14, v3
	v_cvt_f32_ubyte0_e32 v3, v3
	v_mul_f32_e32 v3, 0xbd800000, v3
	v_cmp_eq_f32_e32 vcc, 0, v3
	v_mov_b32_e32 v4, 0x461c4000
	s_mov_b32 s12, 0x3f2aaaab
	s_waitcnt vmcnt(6)
	v_cndmask_b32_e64 v14, v4, 1.0, vcc
	v_frexp_mant_f32_e32 v4, v14
	v_cmp_gt_f32_e64 s[38:39], s12, v4
	s_mov_b32 s12, 0x3f317218
	s_movk_i32 s16, 0x204
	v_cndmask_b32_e64 v5, 1.0, 2.0, s[38:39]
	v_mul_f32_e32 v4, v4, v5
	v_add_f32_e32 v7, 1.0, v4
	v_rcp_f32_e32 v12, v7
	v_add_f32_e32 v5, -1.0, v7
	v_sub_f32_e32 v9, v4, v5
	v_add_f32_e32 v5, -1.0, v4
	v_mul_f32_e32 v13, v5, v12
	v_mul_f32_e32 v6, v7, v13
	v_fma_f32 v8, v13, v7, -v6
	v_fmac_f32_e32 v8, v13, v9
	v_add_f32_e32 v4, v6, v8
	v_sub_f32_e32 v7, v5, v4
	v_pk_add_f32 v[10:11], v[4:5], v[6:7] neg_lo:[0,1] neg_hi:[0,1]
	v_mov_b32_e32 v9, v4
	v_pk_add_f32 v[4:5], v[10:11], v[8:9] neg_lo:[0,1] neg_hi:[0,1]
	v_mov_b32_e32 v8, 0x3e91f4c4
	v_add_f32_e32 v4, v4, v5
	v_add_f32_e32 v4, v7, v4
	v_mul_f32_e32 v5, v12, v4
	v_add_f32_e32 v4, v13, v5
	v_sub_f32_e32 v6, v4, v13
	v_sub_f32_e32 v15, v5, v6
	v_mul_f32_e32 v5, v4, v4
	v_fma_f32 v7, v4, v4, -v5
	v_add_f32_e32 v6, v15, v15
	v_fmac_f32_e32 v7, v4, v6
	v_add_f32_e32 v6, v5, v7
	v_fmamk_f32 v8, v6, 0x3e76c4e1, v8
	v_fmaak_f32 v8, v6, v8, 0x3ecccdef
	v_sub_f32_e32 v5, v6, v5
	v_sub_f32_e32 v16, v7, v5
	v_mul_f32_e32 v5, v6, v8
	v_fma_f32 v7, v6, v8, -v5
	v_fmac_f32_e32 v7, v16, v8
	v_add_f32_e32 v8, v5, v7
	v_add_f32_e32 v9, 0x3f2aaaaa, v8
	v_sub_f32_e32 v5, v8, v5
	v_sub_f32_e32 v5, v7, v5
	v_add_f32_e32 v7, 0xbf2aaaaa, v9
	v_add_f32_e32 v5, 0x31739010, v5
	v_sub_f32_e32 v7, v8, v7
	v_pk_mul_f32 v[10:11], v[4:5], v[6:7]
	v_pk_add_f32 v[12:13], v[4:5], v[6:7]
	v_fma_f32 v8, v6, v4, -v10
	v_fmac_f32_e32 v8, v6, v15
	v_mov_b32_e32 v11, v13
	v_fmac_f32_e32 v8, v16, v4
	v_pk_add_f32 v[6:7], v[10:11], v[8:9]
	v_ldexp_f32 v16, v15, 1
	v_sub_f32_e32 v5, v6, v10
	v_sub_f32_e32 v5, v8, v5
	v_sub_f32_e32 v8, v9, v7
	v_add_f32_e32 v12, v13, v8
	v_pk_mul_f32 v[8:9], v[6:7], v[6:7] op_sel:[0,1] op_sel_hi:[1,0]
	v_cvt_f64_f32_e32 v[10:11], v14
	v_frexp_exp_i32_f64_e32 v9, v[10:11]
	v_subbrev_co_u32_e64 v9, s[38:39], 0, v9, s[38:39]
	v_cvt_f32_i32_e32 v9, v9
	v_fma_f32 v10, v6, v7, -v8
	v_fmac_f32_e32 v10, v6, v12
	v_fmac_f32_e32 v10, v5, v7
	v_mul_f32_e32 v6, 0x3f317218, v9
	v_fma_f32 v12, v9, s12, -v6
	v_fmac_f32_e32 v12, 0xb102e308, v9
	v_ldexp_f32 v13, v4, 1
	v_add_f32_e32 v7, v8, v10
	v_pk_add_f32 v[4:5], v[6:7], v[12:13]
	v_mov_b32_e32 v14, v7
	v_mov_b32_e32 v15, v5
	v_mov_b32_e32 v9, v13
; DEV void phase_prep(const Params& p, char* smem) {
;     ...
;       float inv = powf(10000.f, -(float)(2 * f) / 16.f);
;       float ang = pos * inv;
;       WSP(float, S_ROPEC)[idx] = cosf(ang);
;       WSP(float, S_ROPES)[idx] = sinf(ang);
	v_pk_add_f32 v[8:9], v[14:15], v[8:9] neg_lo:[0,1] neg_hi:[0,1]
	v_mov_b32_e32 v11, v7
	v_pk_add_f32 v[8:9], v[10:11], v[8:9] neg_lo:[0,1] neg_hi:[0,1]
	v_mov_b32_e32 v13, v4
	v_add_f32_e32 v7, v16, v8
	v_add_f32_e32 v7, v7, v9
	v_pk_add_f32 v[8:9], v[4:5], v[6:7] neg_lo:[0,1] neg_hi:[0,1]
	v_pk_add_f32 v[10:11], v[4:5], v[6:7]
	v_mov_b32_e32 v6, v7
	v_mov_b32_e32 v9, v11
	v_pk_add_f32 v[14:15], v[12:13], v[8:9] neg_lo:[0,1] neg_hi:[0,1]
	v_pk_add_f32 v[8:9], v[12:13], v[8:9]
	v_mov_b32_e32 v7, v4
	v_pk_add_f32 v[12:13], v[8:9], v[4:5] op_sel:[1,0] op_sel_hi:[0,1] neg_lo:[0,1] neg_hi:[0,1]
	v_pk_add_f32 v[16:17], v[10:11], v[12:13] op_sel_hi:[1,0] neg_lo:[0,1] neg_hi:[0,1]
	v_mov_b32_e32 v10, v11
	v_mov_b32_e32 v11, v9
	v_pk_mov_b32 v[12:13], v[4:5], v[12:13] op_sel:[1,0]
	v_mov_b32_e32 v16, v14
	v_pk_add_f32 v[10:11], v[10:11], v[12:13] neg_lo:[0,1] neg_hi:[0,1]
	v_mov_b32_e32 v15, v9
	v_pk_add_f32 v[4:5], v[6:7], v[10:11] neg_lo:[0,1] neg_hi:[0,1]
	s_mov_b32 s13, 0x42b17218
	v_pk_add_f32 v[6:7], v[16:17], v[4:5]
	s_mov_b32 s12, 0x3fb8aa3b
	v_pk_add_f32 v[10:11], v[6:7], v[6:7] op_sel:[0,1] op_sel_hi:[1,0]
	s_nop 0
	v_pk_add_f32 v[8:9], v[8:9], v[10:11] op_sel:[1,0] op_sel_hi:[0,1]
	v_mov_b32_e32 v7, v8
	v_pk_add_f32 v[12:13], v[6:7], v[14:15] neg_lo:[0,1] neg_hi:[0,1]
	v_mov_b32_e32 v5, v10
	v_sub_f32_e32 v6, v6, v12
	v_pk_add_f32 v[4:5], v[4:5], v[12:13] neg_lo:[0,1] neg_hi:[0,1]
	v_sub_f32_e32 v6, v14, v6
	v_add_f32_e32 v4, v4, v6
	v_add_f32_e32 v4, v4, v5
	v_add_f32_e32 v5, v8, v4
	v_sub_f32_e32 v6, v5, v8
	v_sub_f32_e32 v4, v4, v6
	v_mul_f32_e32 v6, v3, v5
	v_fma_f32 v5, v3, v5, -v6
	v_fmac_f32_e32 v5, v3, v4
	v_add_f32_e32 v4, v6, v5
	v_cmp_class_f32_e64 s[38:39], v6, s16
	v_sub_f32_e32 v7, v4, v6
	v_sub_f32_e32 v5, v5, v7
	v_cndmask_b32_e64 v4, v4, v6, s[38:39]
	v_cmp_eq_f32_e64 s[38:39], s13, v4
	v_mov_b32_e32 v6, 0x37000000
	s_nop 0
	v_cndmask_b32_e64 v6, 0, v6, s[38:39]
	v_sub_f32_e32 v7, v4, v6
	v_mul_f32_e32 v8, 0x3fb8aa3b, v7
	v_fma_f32 v9, v7, s12, -v8
	v_rndne_f32_e32 v10, v8
	v_fmac_f32_e32 v9, 0x32a5705f, v7
	v_sub_f32_e32 v8, v8, v10
	v_add_f32_e32 v8, v8, v9
	v_exp_f32_e32 v8, v8
	v_cvt_i32_f32_e32 v9, v10
	s_mov_b32 s12, 0x7f800000
	v_cmp_neq_f32_e64 s[38:39], |v4|, s12
	s_mov_b32 s12, 0xc2ce8ed0
	s_nop 0
	v_cndmask_b32_e64 v4, 0, v5, s[38:39]
	v_ldexp_f32 v5, v8, v9
	v_cmp_ngt_f32_e64 s[38:39], s12, v7
	v_add_f32_e32 v4, v6, v4
	s_nop 0
	v_cndmask_b32_e64 v5, 0, v5, s[38:39]
	v_cmp_nlt_f32_e64 s[38:39], s13, v7
	v_cmp_neq_f32_e64 s[12:13], v3, |v3|
	s_nop 0
	v_cndmask_b32_e64 v5, v223, v5, s[38:39]
	v_fma_f32 v4, v5, v4, v5
	v_cmp_class_f32_e64 s[38:39], v5, s16
	s_nop 1
	v_cndmask_b32_e64 v4, v4, v5, s[38:39]
	v_cndmask_b32_e64 v5, v223, 0, s[12:13]
	v_cndmask_b32_e64 v5, v5, 1.0, vcc
	v_cmp_class_f32_e64 s[12:13], v3, s16
	s_nop 1
	v_cndmask_b32_e64 v3, |v4|, v5, s[12:13]
	v_mul_f32_e32 v4, v3, v0
	v_and_b32_e32 v5, 0x7fffffff, v4
	s_brev_b32 s12, 18
	v_lshrrev_b32_e32 v0, 23, v5
	v_and_b32_e32 v3, 0x7fffff, v5
	v_cmp_nlt_f32_e64 s[12:13], |v4|, s12
	v_add_u32_e32 v7, 0xffffff88, v0
	v_or_b32_e32 v6, 0x800000, v3
	s_and_saveexec_b64 s[16:17], s[12:13]
	s_xor_b64 s[16:17], exec, s[16:17]
	s_cbranch_execz .LBB0_1077
	v_cmp_lt_u32_e32 vcc, 63, v7
	s_mov_b32 s42, 0xfe5163ab
	v_mad_u64_u32 v[8:9], s[42:43], v6, s42, 0
	v_cndmask_b32_e32 v0, 0, v230, vcc
	v_add_u32_e32 v0, v0, v7
	v_cmp_lt_u32_e64 s[38:39], 31, v0
	s_mov_b32 s42, 0x3c439041
	s_nop 0
	v_cndmask_b32_e64 v3, 0, v231, s[38:39]
	v_add_u32_e32 v0, v3, v0
	v_cmp_lt_u32_e64 s[40:41], 31, v0
	s_nop 1
	v_cndmask_b32_e64 v3, 0, v231, s[40:41]
	v_add_u32_e32 v3, v3, v0
	v_mov_b32_e32 v0, v9
	v_mad_u64_u32 v[10:11], s[42:43], v6, s42, v[0:1]
	v_mov_b32_e32 v0, v11
	s_mov_b32 s42, 0xdb629599
	v_mad_u64_u32 v[12:13], s[42:43], v6, s42, v[0:1]
	v_mov_b32_e32 v0, v13
	s_mov_b32 s42, 0xf534ddc0
	v_mad_u64_u32 v[14:15], s[42:43], v6, s42, v[0:1]
	v_mov_b32_e32 v0, v15
	s_mov_b32 s42, 0xfc2757d1
	v_mad_u64_u32 v[16:17], s[42:43], v6, s42, v[0:1]
	v_mov_b32_e32 v0, v17
	s_mov_b32 s42, 0x4e441529
	v_mad_u64_u32 v[18:19], s[42:43], v6, s42, v[0:1]
	v_mov_b32_e32 v0, v19
	s_mov_b32 s42, 0xa2f9836e
	v_mad_u64_u32 v[20:21], s[42:43], v6, s42, v[0:1]
	v_cndmask_b32_e32 v9, v18, v14, vcc
	v_cndmask_b32_e32 v0, v20, v16, vcc
	v_cndmask_b32_e32 v13, v21, v18, vcc
	v_cndmask_b32_e64 v11, v0, v9, s[38:39]
	v_cndmask_b32_e64 v0, v13, v0, s[38:39]
	v_cndmask_b32_e32 v13, v16, v12, vcc
	v_cndmask_b32_e64 v9, v9, v13, s[38:39]
	v_sub_u32_e32 v15, 32, v3
	v_cmp_eq_u32_e64 s[42:43], 0, v3
	v_cndmask_b32_e32 v3, v14, v10, vcc
	v_cndmask_b32_e64 v0, v0, v11, s[40:41]
	v_cndmask_b32_e64 v11, v11, v9, s[40:41]
	v_cndmask_b32_e64 v10, v13, v3, s[38:39]
	v_alignbit_b32 v16, v0, v11, v15
	v_cndmask_b32_e64 v9, v9, v10, s[40:41]
	v_cndmask_b32_e64 v0, v16, v0, s[42:43]
	v_alignbit_b32 v13, v11, v9, v15
	v_cndmask_b32_e32 v8, v12, v8, vcc
	v_cndmask_b32_e64 v11, v13, v11, s[42:43]
	v_bfe_u32 v16, v0, 29, 1
	v_cndmask_b32_e64 v3, v3, v8, s[38:39]
	v_alignbit_b32 v13, v0, v11, 30
	v_sub_u32_e32 v17, 0, v16
	v_cndmask_b32_e64 v3, v10, v3, s[40:41]
	v_xor_b32_e32 v13, v13, v17
	v_alignbit_b32 v8, v9, v3, v15
	v_cndmask_b32_e64 v8, v8, v9, s[42:43]
	v_ffbh_u32_e32 v10, v13
	v_alignbit_b32 v9, v11, v8, 30
	v_min_u32_e32 v10, 32, v10
	v_alignbit_b32 v3, v8, v3, 30
	v_xor_b32_e32 v9, v9, v17
	v_sub_u32_e32 v11, 31, v10
	v_xor_b32_e32 v3, v3, v17
	v_alignbit_b32 v12, v13, v9, v11
	v_alignbit_b32 v3, v9, v3, v11
	v_alignbit_b32 v8, v12, v3, 9
	v_ffbh_u32_e32 v9, v8
	v_min_u32_e32 v9, 32, v9
	v_lshrrev_b32_e32 v14, 29, v0
	v_not_b32_e32 v11, v9
	v_alignbit_b32 v3, v8, v3, v11
	v_lshlrev_b32_e32 v8, 31, v14
	v_or_b32_e32 v11, 0x33000000, v8
	v_add_lshl_u32 v9, v9, v10, 23
	v_lshrrev_b32_e32 v3, 9, v3
	v_sub_u32_e32 v9, v11, v9
	v_or_b32_e32 v8, 0.5, v8
	v_lshlrev_b32_e32 v10, 23, v10
	v_or_b32_e32 v3, v9, v3
	v_lshrrev_b32_e32 v9, 9, v12
	v_sub_u32_e32 v8, v8, v10
	v_or_b32_e32 v8, v9, v8
	v_mul_f32_e32 v9, 0x3fc90fda, v8
	s_mov_b32 s38, 0x3fc90fda
	v_fma_f32 v10, v8, s38, -v9
	v_fmac_f32_e32 v10, 0x33a22168, v8
	v_fmac_f32_e32 v10, 0x3fc90fda, v3
	v_lshrrev_b32_e32 v0, 30, v0
	v_add_f32_e32 v8, v9, v10
	v_add_u32_e32 v3, v16, v0
